# swiglu epilogue: bf16 pair packing done with one v_cvt_pk instead of cvt+cvt+shift+or (8 sites per tile)
# baseline (speedup 1.0000x reference)
.LBB0_402:
	s_add_u32 s20, s18, 0xfffc0080
	s_addc_u32 s21, s19, -1
	s_add_i32 s41, 0, 0x10000
	ds_read_b128 v[138:141], v218
	ds_read_b128 v[148:151], v218 offset:1024
	ds_read_b128 v[152:155], v218 offset:2048
	ds_read_b128 v[156:159], v218 offset:3072
	s_cmp_eq_u32 s40, 12
	s_cselect_b32 s23, s1, s21
	s_cselect_b32 s22, s9, s20
	s_cselect_b32 s21, s11, s39
	s_cselect_b32 s20, s33, s38
	s_add_i32 m0, s17, 0xc000
	ds_read_b128 v[160:163], v146
	ds_read_b128 v[164:167], v146 offset:1024
	ds_read_b128 v[168:171], v146 offset:2048
	ds_read_b128 v[172:175], v146 offset:3072
	ds_read_b128 v[176:179], v146 offset:4096
	ds_read_b128 v[180:183], v146 offset:5120
	ds_read_b128 v[184:187], v146 offset:6144
	ds_read_b128 v[188:191], v146 offset:7168
	global_load_lds_dwordx4 v136, s[18:19]
	s_add_i32 m0, s17, 0xe000
	s_nop 0
	global_load_lds_dwordx4 v134, s[18:19]
	s_waitcnt lgkmcnt(8)
	s_barrier
	s_waitcnt lgkmcnt(0)
	v_mfma_f32_16x16x32_bf16 v[124:127], v[138:141], v[160:163], v[124:127]
	v_mfma_f32_16x16x32_bf16 v[116:119], v[152:155], v[160:163], v[116:119]
	v_mfma_f32_16x16x32_bf16 v[108:111], v[138:141], v[168:171], v[108:111]
	v_mfma_f32_16x16x32_bf16 v[100:103], v[152:155], v[168:171], v[100:103]
	v_mfma_f32_16x16x32_bf16 v[92:95], v[138:141], v[176:179], v[92:95]
	v_mfma_f32_16x16x32_bf16 v[84:87], v[152:155], v[176:179], v[84:87]
	v_mfma_f32_16x16x32_bf16 v[76:79], v[138:141], v[184:187], v[76:79]
	v_mfma_f32_16x16x32_bf16 v[68:71], v[152:155], v[184:187], v[68:71]
	v_mfma_f32_16x16x32_bf16 v[124:127], v[148:151], v[164:167], v[124:127]
	v_mfma_f32_16x16x32_bf16 v[116:119], v[156:159], v[164:167], v[116:119]
	v_mfma_f32_16x16x32_bf16 v[108:111], v[148:151], v[172:175], v[108:111]
	v_mfma_f32_16x16x32_bf16 v[100:103], v[156:159], v[172:175], v[100:103]
	v_mfma_f32_16x16x32_bf16 v[92:95], v[148:151], v[180:183], v[92:95]
	v_mfma_f32_16x16x32_bf16 v[84:87], v[156:159], v[180:183], v[84:87]
	v_mfma_f32_16x16x32_bf16 v[76:79], v[148:151], v[188:191], v[76:79]
	v_mfma_f32_16x16x32_bf16 v[68:71], v[156:159], v[188:191], v[68:71]
	s_barrier
	s_add_i32 s44, 0, 0x14000
	s_add_i32 s41, s41, s28
	ds_read_b128 v[198:201], v219
	ds_read_b128 v[206:209], v219 offset:1024
	ds_read_b128 v[210:213], v219 offset:2048
	ds_read_b128 v[214:217], v219 offset:3072
	s_mov_b32 m0, s41
	s_nop 0
	global_load_lds_dwordx4 v192, s[20:21]
	s_add_i32 m0, s41, 0x2000
	s_nop 0
	global_load_lds_dwordx4 v128, s[20:21]
	s_barrier
	s_waitcnt lgkmcnt(0)
	v_mfma_f32_16x16x32_bf16 v[120:123], v[198:201], v[160:163], v[120:123]
	v_mfma_f32_16x16x32_bf16 v[112:115], v[210:213], v[160:163], v[112:115]
	v_mfma_f32_16x16x32_bf16 v[104:107], v[198:201], v[168:171], v[104:107]
	v_mfma_f32_16x16x32_bf16 v[96:99], v[210:213], v[168:171], v[96:99]
	v_mfma_f32_16x16x32_bf16 v[88:91], v[198:201], v[176:179], v[88:91]
	v_mfma_f32_16x16x32_bf16 v[80:83], v[210:213], v[176:179], v[80:83]
	v_mfma_f32_16x16x32_bf16 v[72:75], v[198:201], v[184:187], v[72:75]
	v_mfma_f32_16x16x32_bf16 v[64:67], v[210:213], v[184:187], v[64:67]
	v_mfma_f32_16x16x32_bf16 v[120:123], v[206:209], v[164:167], v[120:123]
	v_mfma_f32_16x16x32_bf16 v[112:115], v[214:217], v[164:167], v[112:115]
	v_mfma_f32_16x16x32_bf16 v[104:107], v[206:209], v[172:175], v[104:107]
	v_mfma_f32_16x16x32_bf16 v[96:99], v[214:217], v[172:175], v[96:99]
	v_mfma_f32_16x16x32_bf16 v[88:91], v[206:209], v[180:183], v[88:91]
	v_mfma_f32_16x16x32_bf16 v[80:83], v[214:217], v[180:183], v[80:83]
	v_mfma_f32_16x16x32_bf16 v[72:75], v[206:209], v[188:191], v[72:75]
	v_mfma_f32_16x16x32_bf16 v[64:67], v[214:217], v[188:191], v[64:67]
	s_mov_b32 m0, s17
	s_add_u32 vcc_lo, s22, 0x80
	s_addc_u32 vcc_hi, s23, 0
	s_barrier
	ds_read_b128 v[160:163], v146 offset:16384
	ds_read_b128 v[164:167], v146 offset:17408
	ds_read_b128 v[168:171], v146 offset:18432
	ds_read_b128 v[172:175], v146 offset:19456
	ds_read_b128 v[176:179], v146 offset:20480
	ds_read_b128 v[180:183], v146 offset:21504
	ds_read_b128 v[184:187], v146 offset:22528
	ds_read_b128 v[188:191], v146 offset:23552
	global_load_lds_dwordx4 v132, s[22:23]
	s_mov_b32 m0, s29
	s_nop 0
	global_load_lds_dwordx4 v130, s[22:23]
	s_barrier
	s_waitcnt lgkmcnt(0)
	v_mfma_f32_16x16x32_bf16 v[60:63], v[138:141], v[160:163], v[60:63]
	v_mfma_f32_16x16x32_bf16 v[52:55], v[152:155], v[160:163], v[52:55]
	v_mfma_f32_16x16x32_bf16 v[44:47], v[138:141], v[168:171], v[44:47]
	v_mfma_f32_16x16x32_bf16 v[36:39], v[152:155], v[168:171], v[36:39]
	v_mfma_f32_16x16x32_bf16 v[28:31], v[138:141], v[176:179], v[28:31]
	v_mfma_f32_16x16x32_bf16 v[20:23], v[152:155], v[176:179], v[20:23]
	v_mfma_f32_16x16x32_bf16 v[12:15], v[138:141], v[184:187], v[12:15]
	v_mfma_f32_16x16x32_bf16 v[4:7], v[152:155], v[184:187], v[4:7]
	v_mfma_f32_16x16x32_bf16 v[60:63], v[148:151], v[164:167], v[60:63]
	v_mfma_f32_16x16x32_bf16 v[52:55], v[156:159], v[164:167], v[52:55]
	v_mfma_f32_16x16x32_bf16 v[44:47], v[148:151], v[172:175], v[44:47]
	v_mfma_f32_16x16x32_bf16 v[36:39], v[156:159], v[172:175], v[36:39]
	v_mfma_f32_16x16x32_bf16 v[28:31], v[148:151], v[180:183], v[28:31]
	v_mfma_f32_16x16x32_bf16 v[20:23], v[156:159], v[180:183], v[20:23]
	v_mfma_f32_16x16x32_bf16 v[12:15], v[148:151], v[188:191], v[12:15]
	v_mfma_f32_16x16x32_bf16 v[4:7], v[156:159], v[188:191], v[4:7]
	s_barrier
	s_add_u32 s42, s20, 0x40000
	s_addc_u32 s43, s21, 0
	s_add_i32 s41, s44, s28
	s_mov_b32 m0, s41
	s_nop 0
	global_load_lds_dwordx4 v192, s[42:43]
	s_add_i32 m0, s41, 0x2000
	s_nop 0
	global_load_lds_dwordx4 v128, s[42:43]
	s_waitcnt vmcnt(6)
	s_barrier
	v_mfma_f32_16x16x32_bf16 v[56:59], v[198:201], v[160:163], v[56:59]
	v_mfma_f32_16x16x32_bf16 v[48:51], v[210:213], v[160:163], v[48:51]
	v_mfma_f32_16x16x32_bf16 v[40:43], v[198:201], v[168:171], v[40:43]
	v_mfma_f32_16x16x32_bf16 v[32:35], v[210:213], v[168:171], v[32:35]
	v_mfma_f32_16x16x32_bf16 v[24:27], v[198:201], v[176:179], v[24:27]
	v_mfma_f32_16x16x32_bf16 v[16:19], v[210:213], v[176:179], v[16:19]
	v_mfma_f32_16x16x32_bf16 v[8:11], v[198:201], v[184:187], v[8:11]
	v_mfma_f32_16x16x32_bf16 v[0:3], v[210:213], v[184:187], v[0:3]
	v_mfma_f32_16x16x32_bf16 v[56:59], v[206:209], v[164:167], v[56:59]
	v_mfma_f32_16x16x32_bf16 v[48:51], v[214:217], v[164:167], v[48:51]
	v_mfma_f32_16x16x32_bf16 v[40:43], v[206:209], v[172:175], v[40:43]
	v_mfma_f32_16x16x32_bf16 v[32:35], v[214:217], v[172:175], v[32:35]
	v_mfma_f32_16x16x32_bf16 v[24:27], v[206:209], v[180:183], v[24:27]
	v_mfma_f32_16x16x32_bf16 v[16:19], v[214:217], v[180:183], v[16:19]
	v_mfma_f32_16x16x32_bf16 v[8:11], v[206:209], v[188:191], v[8:11]
	v_mfma_f32_16x16x32_bf16 v[0:3], v[214:217], v[188:191], v[0:3]
	s_add_i32 s41, 0, 0x18000
	s_barrier
	ds_read_b128 v[138:141], v220
	ds_read_b128 v[148:151], v220 offset:1024
	ds_read_b128 v[152:155], v220 offset:2048
	ds_read_b128 v[156:159], v220 offset:3072
	s_add_u32 s22, s22, 0x40000
	s_addc_u32 s23, s23, 0
	s_mov_b32 m0, s30
	ds_read_b128 v[160:163], v146 offset:32768
	ds_read_b128 v[164:167], v146 offset:33792
	ds_read_b128 v[168:171], v146 offset:34816
	ds_read_b128 v[172:175], v146 offset:35840
	ds_read_b128 v[176:179], v146 offset:36864
	ds_read_b128 v[180:183], v146 offset:37888
	ds_read_b128 v[184:187], v146 offset:38912
	ds_read_b128 v[188:191], v146 offset:39936
	global_load_lds_dwordx4 v132, s[22:23]
	s_mov_b32 m0, s31
	s_nop 0
	global_load_lds_dwordx4 v130, s[22:23]
	s_waitcnt lgkmcnt(8)
	s_barrier
	s_waitcnt lgkmcnt(0)
	v_mfma_f32_16x16x32_bf16 v[124:127], v[138:141], v[160:163], v[124:127]
	v_mfma_f32_16x16x32_bf16 v[116:119], v[152:155], v[160:163], v[116:119]
	v_mfma_f32_16x16x32_bf16 v[108:111], v[138:141], v[168:171], v[108:111]
	v_mfma_f32_16x16x32_bf16 v[100:103], v[152:155], v[168:171], v[100:103]
	v_mfma_f32_16x16x32_bf16 v[92:95], v[138:141], v[176:179], v[92:95]
	v_mfma_f32_16x16x32_bf16 v[84:87], v[152:155], v[176:179], v[84:87]
	v_mfma_f32_16x16x32_bf16 v[76:79], v[138:141], v[184:187], v[76:79]
	v_mfma_f32_16x16x32_bf16 v[68:71], v[152:155], v[184:187], v[68:71]
	v_mfma_f32_16x16x32_bf16 v[124:127], v[148:151], v[164:167], v[124:127]
	v_mfma_f32_16x16x32_bf16 v[116:119], v[156:159], v[164:167], v[116:119]
	v_mfma_f32_16x16x32_bf16 v[108:111], v[148:151], v[172:175], v[108:111]
	v_mfma_f32_16x16x32_bf16 v[100:103], v[156:159], v[172:175], v[100:103]
	v_mfma_f32_16x16x32_bf16 v[92:95], v[148:151], v[180:183], v[92:95]
	v_mfma_f32_16x16x32_bf16 v[84:87], v[156:159], v[180:183], v[84:87]
	v_mfma_f32_16x16x32_bf16 v[76:79], v[148:151], v[188:191], v[76:79]
	v_mfma_f32_16x16x32_bf16 v[68:71], v[156:159], v[188:191], v[68:71]
	s_barrier
	s_add_i32 s22, 0, 0x1c000
	s_add_i32 s23, s41, s28
	s_add_u32 s100, s20, 0x80
	s_addc_u32 s101, s21, 0
	s_mov_b32 m0, s23
	ds_read_b128 v[198:201], v221
	ds_read_b128 v[206:209], v221 offset:1024
	ds_read_b128 v[210:213], v221 offset:2048
	ds_read_b128 v[214:217], v221 offset:3072
	global_load_lds_dwordx4 v192, s[100:101]
	s_add_i32 m0, s23, 0x2000
	s_nop 0
	global_load_lds_dwordx4 v128, s[100:101]
	s_barrier
	s_waitcnt lgkmcnt(0)
	v_mfma_f32_16x16x32_bf16 v[120:123], v[198:201], v[160:163], v[120:123]
	v_mfma_f32_16x16x32_bf16 v[112:115], v[210:213], v[160:163], v[112:115]
	v_mfma_f32_16x16x32_bf16 v[104:107], v[198:201], v[168:171], v[104:107]
	v_mfma_f32_16x16x32_bf16 v[96:99], v[210:213], v[168:171], v[96:99]
	v_mfma_f32_16x16x32_bf16 v[88:91], v[198:201], v[176:179], v[88:91]
	v_mfma_f32_16x16x32_bf16 v[80:83], v[210:213], v[176:179], v[80:83]
	v_mfma_f32_16x16x32_bf16 v[72:75], v[198:201], v[184:187], v[72:75]
	v_mfma_f32_16x16x32_bf16 v[64:67], v[210:213], v[184:187], v[64:67]
	v_mfma_f32_16x16x32_bf16 v[120:123], v[206:209], v[164:167], v[120:123]
	v_mfma_f32_16x16x32_bf16 v[112:115], v[214:217], v[164:167], v[112:115]
	v_mfma_f32_16x16x32_bf16 v[104:107], v[206:209], v[172:175], v[104:107]
	v_mfma_f32_16x16x32_bf16 v[96:99], v[214:217], v[172:175], v[96:99]
	v_mfma_f32_16x16x32_bf16 v[88:91], v[206:209], v[180:183], v[88:91]
	v_mfma_f32_16x16x32_bf16 v[80:83], v[214:217], v[180:183], v[80:83]
	v_mfma_f32_16x16x32_bf16 v[72:75], v[206:209], v[188:191], v[72:75]
	v_mfma_f32_16x16x32_bf16 v[64:67], v[214:217], v[188:191], v[64:67]
	s_mov_b32 m0, s34
	s_barrier
	ds_read_b128 v[160:163], v146 offset:49152
	ds_read_b128 v[164:167], v146 offset:50176
	ds_read_b128 v[168:171], v146 offset:51200
	ds_read_b128 v[172:175], v146 offset:52224
	ds_read_b128 v[176:179], v146 offset:53248
	ds_read_b128 v[180:183], v146 offset:54272
	ds_read_b128 v[184:187], v146 offset:55296
	ds_read_b128 v[188:191], v146 offset:56320
	global_load_lds_dwordx4 v132, vcc
	s_mov_b32 m0, s35
	s_nop 0
	global_load_lds_dwordx4 v130, vcc
	s_barrier
	s_waitcnt lgkmcnt(0)
	v_mfma_f32_16x16x32_bf16 v[60:63], v[138:141], v[160:163], v[60:63]
	v_mfma_f32_16x16x32_bf16 v[52:55], v[152:155], v[160:163], v[52:55]
	v_mfma_f32_16x16x32_bf16 v[44:47], v[138:141], v[168:171], v[44:47]
	v_mfma_f32_16x16x32_bf16 v[36:39], v[152:155], v[168:171], v[36:39]
	v_mfma_f32_16x16x32_bf16 v[28:31], v[138:141], v[176:179], v[28:31]
	v_mfma_f32_16x16x32_bf16 v[20:23], v[152:155], v[176:179], v[20:23]
	v_mfma_f32_16x16x32_bf16 v[12:15], v[138:141], v[184:187], v[12:15]
	v_mfma_f32_16x16x32_bf16 v[4:7], v[152:155], v[184:187], v[4:7]
	v_mfma_f32_16x16x32_bf16 v[60:63], v[148:151], v[164:167], v[60:63]
	v_mfma_f32_16x16x32_bf16 v[52:55], v[156:159], v[164:167], v[52:55]
	v_mfma_f32_16x16x32_bf16 v[44:47], v[148:151], v[172:175], v[44:47]
	v_mfma_f32_16x16x32_bf16 v[36:39], v[156:159], v[172:175], v[36:39]
	v_mfma_f32_16x16x32_bf16 v[28:31], v[148:151], v[180:183], v[28:31]
	v_mfma_f32_16x16x32_bf16 v[20:23], v[156:159], v[180:183], v[20:23]
	v_mfma_f32_16x16x32_bf16 v[12:15], v[148:151], v[188:191], v[12:15]
	v_mfma_f32_16x16x32_bf16 v[4:7], v[156:159], v[188:191], v[4:7]
	s_barrier
	s_add_u32 s20, s20, 0x40080
	s_addc_u32 s21, s21, 0
	s_add_i32 s22, s22, s28
	s_mov_b32 m0, s22
	s_nop 0
	global_load_lds_dwordx4 v192, s[20:21]
	s_add_i32 m0, s22, 0x2000
	s_nop 0
	global_load_lds_dwordx4 v128, s[20:21]
	s_waitcnt vmcnt(6)
	s_barrier
	v_mfma_f32_16x16x32_bf16 v[56:59], v[198:201], v[160:163], v[56:59]
	v_mfma_f32_16x16x32_bf16 v[48:51], v[210:213], v[160:163], v[48:51]
	v_mfma_f32_16x16x32_bf16 v[40:43], v[198:201], v[168:171], v[40:43]
	v_mfma_f32_16x16x32_bf16 v[32:35], v[210:213], v[168:171], v[32:35]
	v_mfma_f32_16x16x32_bf16 v[24:27], v[198:201], v[176:179], v[24:27]
	v_mfma_f32_16x16x32_bf16 v[16:19], v[210:213], v[176:179], v[16:19]
	v_mfma_f32_16x16x32_bf16 v[8:11], v[198:201], v[184:187], v[8:11]
	v_mfma_f32_16x16x32_bf16 v[0:3], v[210:213], v[184:187], v[0:3]
	v_mfma_f32_16x16x32_bf16 v[56:59], v[206:209], v[164:167], v[56:59]
	v_mfma_f32_16x16x32_bf16 v[48:51], v[214:217], v[164:167], v[48:51]
	v_mfma_f32_16x16x32_bf16 v[40:43], v[206:209], v[172:175], v[40:43]
	v_mfma_f32_16x16x32_bf16 v[32:35], v[214:217], v[172:175], v[32:35]
	v_mfma_f32_16x16x32_bf16 v[24:27], v[206:209], v[180:183], v[24:27]
	v_mfma_f32_16x16x32_bf16 v[16:19], v[214:217], v[180:183], v[16:19]
	v_mfma_f32_16x16x32_bf16 v[8:11], v[206:209], v[188:191], v[8:11]
	v_mfma_f32_16x16x32_bf16 v[0:3], v[214:217], v[188:191], v[0:3]
	s_add_i32 s40, s40, 2
	s_add_u32 s38, s38, 0x100
	s_addc_u32 s39, s39, 0
	s_add_u32 s18, s18, 0x100
	s_addc_u32 s19, s19, 0
	s_cmp_gt_u32 s40, 13
	s_barrier
	s_cbranch_scc0 .LBB0_402
	v_mov_b32_e32 v139, v252
	s_lshl_b32 s9, s16, 8
	v_readfirstlane_b32 s1, v139
	s_ashr_i32 s11, s1, 2
	s_andn2_b32 s11, s11, 63
	s_lshr_b32 s1, s1, 1
	s_add_i32 s11, s11, s9
	s_lshl_b32 s0, s0, 7
	s_and_b32 s1, s1, 0x60
	v_and_or_b32 v138, v139, 15, s11
	s_or_b32 s0, s1, s0
	v_lshrrev_b32_e32 v139, 1, v139
	v_and_or_b32 v142, v139, 24, s0
	v_ashrrev_i32_e32 v139, 31, v138
	v_lshl_add_u64 v[140:141], v[138:139], 2, s[6:7]
	v_pk_mul_f32 v[120:121], v[124:125], v[120:121]
	v_pk_mul_f32 v[122:123], v[126:127], v[122:123]
	v_pk_mul_f32 v[112:113], v[116:117], v[112:113]
	v_pk_mul_f32 v[114:115], v[118:119], v[114:115]
	v_ashrrev_i32_e32 v143, 31, v142
	s_movk_i32 s9, 0x1600
	v_pk_mul_f32 v[104:105], v[108:109], v[104:105]
	v_pk_mul_f32 v[106:107], v[110:111], v[106:107]
	v_pk_mul_f32 v[96:97], v[100:101], v[96:97]
	v_or_b32_e32 v150, 16, v138
	v_pk_mul_f32 v[98:99], v[102:103], v[98:99]
	v_pk_mul_f32 v[88:89], v[92:93], v[88:89]
	v_pk_mul_f32 v[90:91], v[94:95], v[90:91]
	v_pk_mul_f32 v[80:81], v[84:85], v[80:81]
	v_or_b32_e32 v148, 32, v138
	v_pk_mul_f32 v[82:83], v[86:87], v[82:83]
	v_pk_mul_f32 v[72:73], v[76:77], v[72:73]
	v_pk_mul_f32 v[74:75], v[78:79], v[74:75]
	v_pk_mul_f32 v[64:65], v[68:69], v[64:65]
	v_or_b32_e32 v139, 48, v138
	v_pk_mul_f32 v[66:67], v[70:71], v[66:67]
	v_pk_mul_f32 v[56:57], v[60:61], v[56:57]
	v_pk_mul_f32 v[58:59], v[62:63], v[58:59]
	v_pk_mul_f32 v[48:49], v[52:53], v[48:49]
	v_pk_mul_f32 v[50:51], v[54:55], v[50:51]
	v_pk_mul_f32 v[40:41], v[44:45], v[40:41]
	v_pk_mul_f32 v[42:43], v[46:47], v[42:43]
	v_pk_mul_f32 v[32:33], v[36:37], v[32:33]
	v_pk_mul_f32 v[34:35], v[38:39], v[34:35]
	v_pk_mul_f32 v[24:25], v[28:29], v[24:25]
	v_pk_mul_f32 v[26:27], v[30:31], v[26:27]
	v_pk_mul_f32 v[16:17], v[20:21], v[16:17]
	v_pk_mul_f32 v[18:19], v[22:23], v[18:19]
	v_pk_mul_f32 v[8:9], v[12:13], v[8:9]
	v_pk_mul_f32 v[10:11], v[14:15], v[10:11]
	v_pk_mul_f32 v[0:1], v[4:5], v[0:1]
	v_pk_mul_f32 v[2:3], v[6:7], v[2:3]
	s_mov_b32 s16, s8
	s_mov_b64 s[18:19], s[14:15]
	s_mov_b64 s[20:21], s[12:13]
	v_fmamk_f32 v239, v231, 0x3a800000, v194
	s_nop 0
	v_rsq_f32_e32 v144, v239
	s_nop 0
	v_mul_f32_e32 v152, 0xbfb8aa3b, v144
	v_pk_mul_f32 v[156:157], v[124:125], v[152:153] op_sel_hi:[1,0]
	v_pk_mul_f32 v[154:155], v[126:127], v[152:153] op_sel_hi:[1,0]
	v_exp_f32_e32 v153, v156
	s_nop 0
	v_fma_f32 v153, v153, v239, v239
	v_rcp_f32_e32 v156, v153
	v_exp_f32_e32 v153, v157
	s_nop 0
	v_fma_f32 v153, v153, v239, v239
	v_rcp_f32_e32 v157, v153
	v_exp_f32_e32 v153, v154
	s_nop 0
	v_fma_f32 v153, v153, v239, v239
	v_rcp_f32_e32 v154, v153
	v_exp_f32_e32 v153, v155
	v_pk_mul_f32 v[120:121], v[120:121], v[156:157]
	v_fma_f32 v153, v153, v239, v239
	v_rcp_f32_e32 v155, v153
	v_cvt_pk_bf16_f32 v120, v120, v121
	v_readlane_b32 s0, v254, 29
	s_nop 0
	v_pk_mul_f32 v[122:123], v[122:123], v[154:155]
	v_readlane_b32 s1, v254, 30
	v_cvt_pk_bf16_f32 v121, v122, v123
	v_pk_mul_f32 v[124:125], v[116:117], v[152:153] op_sel_hi:[1,0]
	v_pk_mul_f32 v[122:123], v[118:119], v[152:153] op_sel_hi:[1,0]
	v_exp_f32_e32 v124, v124
	v_exp_f32_e32 v125, v125
	v_exp_f32_e32 v122, v122
	v_exp_f32_e32 v123, v123
	v_fma_f32 v124, v124, v239, v239
	v_fma_f32 v125, v125, v239, v239
	v_rcp_f32_e32 v124, v124
	v_rcp_f32_e32 v125, v125
	v_fma_f32 v122, v122, v239, v239
	v_fma_f32 v123, v123, v239, v239
	v_rcp_f32_e32 v122, v122
	v_rcp_f32_e32 v123, v123
	s_nop 0
	v_pk_mul_f32 v[112:113], v[112:113], v[124:125]
	s_nop 0
	v_pk_mul_f32 v[114:115], v[114:115], v[122:123]
	v_cvt_pk_bf16_f32 v122, v112, v113
	v_mov_b64_e32 v[112:113], s[0:1]
	v_cvt_pk_bf16_f32 v123, v114, v115
	v_mad_i64_i32 v[116:117], s[0:1], v138, s9, v[112:113]
	v_lshlrev_b64 v[114:115], 1, v[142:143]
	v_lshl_add_u64 v[116:117], v[116:117], 0, v[114:115]
	global_store_dwordx4 v[116:117], v[120:123], off
	v_fmamk_f32 v239, v232, 0x3a800000, v194
	s_nop 0
	v_rsq_f32_e32 v116, v239
	s_nop 0
	v_mul_f32_e32 v118, 0xbfb8aa3b, v116
	v_pk_mul_f32 v[120:121], v[108:109], v[118:119] op_sel_hi:[1,0]
	v_pk_mul_f32 v[122:123], v[110:111], v[118:119] op_sel_hi:[1,0]
	v_exp_f32_e32 v117, v120
	s_nop 0
	v_fma_f32 v117, v117, v239, v239
	v_rcp_f32_e32 v120, v117
	v_exp_f32_e32 v117, v121
	s_nop 0
	v_fma_f32 v117, v117, v239, v239
	v_rcp_f32_e32 v121, v117
	v_exp_f32_e32 v117, v122
	s_nop 0
	v_fma_f32 v117, v117, v239, v239
	v_rcp_f32_e32 v122, v117
	v_exp_f32_e32 v117, v123
	s_nop 0
	v_fma_f32 v117, v117, v239, v239
	v_rcp_f32_e32 v123, v117
	s_nop 0
	v_pk_mul_f32 v[104:105], v[104:105], v[120:121]
	s_nop 0
	v_pk_mul_f32 v[106:107], v[106:107], v[122:123]
	v_cvt_pk_bf16_f32 v104, v104, v105
	v_cvt_pk_bf16_f32 v105, v106, v107
	v_pk_mul_f32 v[108:109], v[100:101], v[118:119] op_sel_hi:[1,0]
	v_pk_mul_f32 v[106:107], v[102:103], v[118:119] op_sel_hi:[1,0]
	v_exp_f32_e32 v108, v108
	v_exp_f32_e32 v109, v109
	v_exp_f32_e32 v106, v106
	v_exp_f32_e32 v107, v107
	v_fma_f32 v108, v108, v239, v239
	v_fma_f32 v109, v109, v239, v239
	v_rcp_f32_e32 v108, v108
	v_rcp_f32_e32 v109, v109
	v_fma_f32 v106, v106, v239, v239
	v_fma_f32 v107, v107, v239, v239
	v_rcp_f32_e32 v106, v106
	v_rcp_f32_e32 v107, v107
	s_nop 0
	v_pk_mul_f32 v[96:97], v[96:97], v[108:109]
	s_nop 0
	v_pk_mul_f32 v[98:99], v[98:99], v[106:107]
	v_cvt_pk_bf16_f32 v106, v96, v97
	v_mad_i64_i32 v[96:97], s[0:1], v150, s9, v[112:113]
	v_cvt_pk_bf16_f32 v107, v98, v99
	v_lshl_add_u64 v[96:97], v[96:97], 0, v[114:115]
	global_store_dwordx4 v[96:97], v[104:107], off
	v_fmamk_f32 v239, v233, 0x3a800000, v194
	s_nop 0
	v_rsq_f32_e32 v96, v239
	s_nop 0
	v_mov_b32_e32 v97, v96
	v_mul_f32_e32 v96, 0xbfb8aa3b, v97
	v_pk_mul_f32 v[102:103], v[92:93], v[96:97] op_sel_hi:[1,0]
	s_nop 0
	v_pk_mul_f32 v[100:101], v[94:95], v[96:97] op_sel_hi:[1,0]
	v_exp_f32_e32 v97, v102
	s_nop 0
	v_fma_f32 v97, v97, v239, v239
	v_rcp_f32_e32 v102, v97
	v_exp_f32_e32 v97, v103
	s_nop 0
	v_fma_f32 v97, v97, v239, v239
	v_rcp_f32_e32 v103, v97
	v_exp_f32_e32 v97, v100
	s_nop 0
	v_fma_f32 v97, v97, v239, v239
	v_rcp_f32_e32 v100, v97
	v_exp_f32_e32 v97, v101
	v_pk_mul_f32 v[88:89], v[88:89], v[102:103]
	v_fma_f32 v97, v97, v239, v239
	v_rcp_f32_e32 v101, v97
	v_cvt_pk_bf16_f32 v88, v88, v89
	s_nop 0
	v_pk_mul_f32 v[90:91], v[90:91], v[100:101]
	s_nop 0
	v_cvt_pk_bf16_f32 v89, v90, v91
	v_pk_mul_f32 v[92:93], v[84:85], v[96:97] op_sel_hi:[1,0]
	v_pk_mul_f32 v[90:91], v[86:87], v[96:97] op_sel_hi:[1,0]
	v_exp_f32_e32 v92, v92
	v_exp_f32_e32 v93, v93
	v_exp_f32_e32 v90, v90
	v_exp_f32_e32 v91, v91
	v_fma_f32 v92, v92, v239, v239
	v_fma_f32 v93, v93, v239, v239
	v_rcp_f32_e32 v92, v92
	v_rcp_f32_e32 v93, v93
	v_fma_f32 v90, v90, v239, v239
	v_fma_f32 v91, v91, v239, v239
	v_rcp_f32_e32 v90, v90
	v_rcp_f32_e32 v91, v91
	s_nop 0
	v_pk_mul_f32 v[80:81], v[80:81], v[92:93]
	s_nop 0
	v_pk_mul_f32 v[82:83], v[82:83], v[90:91]
	v_cvt_pk_bf16_f32 v90, v80, v81
	v_mad_i64_i32 v[80:81], s[0:1], v148, s9, v[112:113]
	v_cvt_pk_bf16_f32 v91, v82, v83
	v_lshl_add_u64 v[80:81], v[80:81], 0, v[114:115]
	global_store_dwordx4 v[80:81], v[88:91], off
	v_fmamk_f32 v239, v234, 0x3a800000, v194
	s_nop 0
	v_rsq_f32_e32 v80, v239
	s_nop 0
	v_mov_b32_e32 v81, v80
	v_mul_f32_e32 v80, 0xbfb8aa3b, v81
	v_pk_mul_f32 v[86:87], v[76:77], v[80:81] op_sel_hi:[1,0]
	s_nop 0
	v_pk_mul_f32 v[84:85], v[78:79], v[80:81] op_sel_hi:[1,0]
	v_exp_f32_e32 v81, v86
	s_nop 0
	v_fma_f32 v81, v81, v239, v239
	v_rcp_f32_e32 v86, v81
	v_exp_f32_e32 v81, v87
	s_nop 0
	v_fma_f32 v81, v81, v239, v239
	v_rcp_f32_e32 v87, v81
	v_exp_f32_e32 v81, v84
	s_nop 0
	v_fma_f32 v81, v81, v239, v239
	v_rcp_f32_e32 v84, v81
	v_exp_f32_e32 v81, v85
	v_pk_mul_f32 v[72:73], v[72:73], v[86:87]
	v_fma_f32 v81, v81, v239, v239
	v_rcp_f32_e32 v85, v81
	v_cvt_pk_bf16_f32 v72, v72, v73
	s_nop 0
	v_pk_mul_f32 v[74:75], v[74:75], v[84:85]
	s_nop 0
	v_cvt_pk_bf16_f32 v73, v74, v75
	v_pk_mul_f32 v[76:77], v[68:69], v[80:81] op_sel_hi:[1,0]
	v_pk_mul_f32 v[74:75], v[70:71], v[80:81] op_sel_hi:[1,0]
	v_exp_f32_e32 v76, v76
	v_exp_f32_e32 v77, v77
	v_exp_f32_e32 v74, v74
	v_exp_f32_e32 v75, v75
	v_fma_f32 v76, v76, v239, v239
	v_fma_f32 v77, v77, v239, v239
	v_rcp_f32_e32 v76, v76
	v_rcp_f32_e32 v77, v77
	v_fma_f32 v74, v74, v239, v239
	v_fma_f32 v75, v75, v239, v239
	v_rcp_f32_e32 v74, v74
	v_rcp_f32_e32 v75, v75
	s_nop 0
	v_pk_mul_f32 v[64:65], v[64:65], v[76:77]
	v_add_u32_e32 v69, 0x90, v138
	s_nop 0
	v_pk_mul_f32 v[66:67], v[66:67], v[74:75]
	v_cvt_pk_bf16_f32 v74, v64, v65
	v_mad_i64_i32 v[64:65], s[0:1], v139, s9, v[112:113]
	v_cvt_pk_bf16_f32 v75, v66, v67
	v_lshl_add_u64 v[64:65], v[64:65], 0, v[114:115]
	global_store_dwordx4 v[64:65], v[72:75], off
	v_add_u32_e32 v67, 0x80, v138
	v_add_u32_e32 v66, 0xa0, v138
	v_add_u32_e32 v64, 0xb0, v138
	v_fmamk_f32 v239, v235, 0x3a800000, v194
	s_nop 0
	v_rsq_f32_e32 v68, v239
	s_nop 0
	v_mov_b32_e32 v70, v68
	v_mul_f32_e32 v68, 0xbfb8aa3b, v70
	v_pk_mul_f32 v[74:75], v[60:61], v[68:69] op_sel_hi:[1,0]
	v_pk_mul_f32 v[72:73], v[62:63], v[68:69] op_sel_hi:[1,0]
	v_exp_f32_e32 v74, v74
	v_exp_f32_e32 v75, v75
	v_exp_f32_e32 v72, v72
	v_exp_f32_e32 v73, v73
	v_fma_f32 v74, v74, v239, v239
	v_fma_f32 v75, v75, v239, v239
	v_rcp_f32_e32 v74, v74
	v_rcp_f32_e32 v75, v75
	v_fma_f32 v72, v72, v239, v239
	v_fma_f32 v73, v73, v239, v239
	v_rcp_f32_e32 v72, v72
	v_rcp_f32_e32 v73, v73
	s_nop 0
	s_nop 0
	v_pk_mul_f32 v[56:57], v[56:57], v[74:75]
	s_nop 0
	v_pk_mul_f32 v[58:59], v[58:59], v[72:73]
	v_cvt_pk_bf16_f32 v56, v56, v57
	v_cvt_pk_bf16_f32 v57, v58, v59
	v_pk_mul_f32 v[60:61], v[52:53], v[68:69] op_sel_hi:[1,0]
	v_pk_mul_f32 v[58:59], v[54:55], v[68:69] op_sel_hi:[1,0]
	v_exp_f32_e32 v60, v60
	v_exp_f32_e32 v61, v61
	v_exp_f32_e32 v58, v58
	v_exp_f32_e32 v59, v59
	v_fma_f32 v60, v60, v239, v239
	v_fma_f32 v61, v61, v239, v239
	v_rcp_f32_e32 v60, v60
	v_rcp_f32_e32 v61, v61
	v_fma_f32 v58, v58, v239, v239
	v_fma_f32 v59, v59, v239, v239
	v_rcp_f32_e32 v58, v58
	v_rcp_f32_e32 v59, v59
	s_nop 0
	v_pk_mul_f32 v[48:49], v[48:49], v[60:61]
	s_nop 0
	v_pk_mul_f32 v[50:51], v[50:51], v[58:59]
	v_cvt_pk_bf16_f32 v58, v48, v49
	v_mad_i64_i32 v[48:49], s[0:1], v67, s9, v[112:113]
	v_cvt_pk_bf16_f32 v59, v50, v51
	v_lshl_add_u64 v[48:49], v[48:49], 0, v[114:115]
	global_store_dwordx4 v[48:49], v[56:59], off
	v_fmamk_f32 v239, v236, 0x3a800000, v194
	s_nop 0
	v_rsq_f32_e32 v48, v239
	s_nop 0
	v_mov_b32_e32 v49, v48
	v_mul_f32_e32 v48, 0xbfb8aa3b, v49
	v_pk_mul_f32 v[54:55], v[44:45], v[48:49] op_sel_hi:[1,0]
	s_nop 0
	v_pk_mul_f32 v[52:53], v[46:47], v[48:49] op_sel_hi:[1,0]
	v_exp_f32_e32 v49, v54
	s_nop 0
	v_fma_f32 v49, v49, v239, v239
	v_rcp_f32_e32 v54, v49
	v_exp_f32_e32 v49, v55
	s_nop 0
	v_fma_f32 v49, v49, v239, v239
	v_rcp_f32_e32 v55, v49
	v_exp_f32_e32 v49, v52
	s_nop 0
	v_fma_f32 v49, v49, v239, v239
	v_rcp_f32_e32 v52, v49
	v_exp_f32_e32 v49, v53
	v_pk_mul_f32 v[40:41], v[40:41], v[54:55]
	v_fma_f32 v49, v49, v239, v239
	v_rcp_f32_e32 v53, v49
	v_cvt_pk_bf16_f32 v40, v40, v41
	s_nop 0
	v_pk_mul_f32 v[42:43], v[42:43], v[52:53]
	s_nop 0
	v_cvt_pk_bf16_f32 v41, v42, v43
	v_pk_mul_f32 v[44:45], v[36:37], v[48:49] op_sel_hi:[1,0]
	v_pk_mul_f32 v[42:43], v[38:39], v[48:49] op_sel_hi:[1,0]
	v_exp_f32_e32 v44, v44
	v_exp_f32_e32 v45, v45
	v_exp_f32_e32 v42, v42
	v_exp_f32_e32 v43, v43
	v_fma_f32 v44, v44, v239, v239
	v_fma_f32 v45, v45, v239, v239
	v_rcp_f32_e32 v44, v44
	v_rcp_f32_e32 v45, v45
	v_fma_f32 v42, v42, v239, v239
	v_fma_f32 v43, v43, v239, v239
	v_rcp_f32_e32 v42, v42
	v_rcp_f32_e32 v43, v43
	s_nop 0
	v_pk_mul_f32 v[32:33], v[32:33], v[44:45]
	s_nop 0
	v_pk_mul_f32 v[34:35], v[34:35], v[42:43]
	v_cvt_pk_bf16_f32 v42, v32, v33
	v_mad_i64_i32 v[32:33], s[0:1], v69, s9, v[112:113]
	v_cvt_pk_bf16_f32 v43, v34, v35
	v_lshl_add_u64 v[32:33], v[32:33], 0, v[114:115]
	global_store_dwordx4 v[32:33], v[40:43], off
	v_fmamk_f32 v239, v237, 0x3a800000, v194
	s_nop 0
	v_rsq_f32_e32 v32, v239
	s_nop 0
	v_mov_b32_e32 v33, v32
	v_mul_f32_e32 v32, 0xbfb8aa3b, v33
	v_pk_mul_f32 v[38:39], v[28:29], v[32:33] op_sel_hi:[1,0]
	s_nop 0
	v_pk_mul_f32 v[36:37], v[30:31], v[32:33] op_sel_hi:[1,0]
	v_exp_f32_e32 v33, v38
	s_nop 0
	v_fma_f32 v33, v33, v239, v239
	v_rcp_f32_e32 v38, v33
	v_exp_f32_e32 v33, v39
	s_nop 0
	v_fma_f32 v33, v33, v239, v239
	v_rcp_f32_e32 v39, v33
	v_exp_f32_e32 v33, v36
	s_nop 0
	v_fma_f32 v33, v33, v239, v239
	v_rcp_f32_e32 v36, v33
	v_exp_f32_e32 v33, v37
	v_pk_mul_f32 v[24:25], v[24:25], v[38:39]
	v_fma_f32 v33, v33, v239, v239
	v_rcp_f32_e32 v37, v33
	v_cvt_pk_bf16_f32 v24, v24, v25
	s_nop 0
	v_pk_mul_f32 v[26:27], v[26:27], v[36:37]
	s_nop 0
	v_cvt_pk_bf16_f32 v25, v26, v27
	v_pk_mul_f32 v[28:29], v[20:21], v[32:33] op_sel_hi:[1,0]
	v_pk_mul_f32 v[26:27], v[22:23], v[32:33] op_sel_hi:[1,0]
	v_exp_f32_e32 v28, v28
	v_exp_f32_e32 v29, v29
	v_exp_f32_e32 v26, v26
	v_exp_f32_e32 v27, v27
	v_fma_f32 v28, v28, v239, v239
	v_fma_f32 v29, v29, v239, v239
	v_rcp_f32_e32 v28, v28
	v_rcp_f32_e32 v29, v29
	v_fma_f32 v26, v26, v239, v239
	v_fma_f32 v27, v27, v239, v239
	v_rcp_f32_e32 v26, v26
	v_rcp_f32_e32 v27, v27
	s_nop 0
	v_pk_mul_f32 v[16:17], v[16:17], v[28:29]
	s_nop 0
	v_pk_mul_f32 v[18:19], v[18:19], v[26:27]
	v_cvt_pk_bf16_f32 v26, v16, v17
	v_mad_i64_i32 v[16:17], s[0:1], v66, s9, v[112:113]
	v_cvt_pk_bf16_f32 v27, v18, v19
	v_lshl_add_u64 v[16:17], v[16:17], 0, v[114:115]
	global_store_dwordx4 v[16:17], v[24:27], off
	v_fmamk_f32 v239, v238, 0x3a800000, v194
	s_nop 0
	v_rsq_f32_e32 v16, v239
	s_nop 0
	v_mov_b32_e32 v17, v16
	v_mul_f32_e32 v16, 0xbfb8aa3b, v17
	v_pk_mul_f32 v[22:23], v[12:13], v[16:17] op_sel_hi:[1,0]
	s_nop 0
	v_pk_mul_f32 v[20:21], v[14:15], v[16:17] op_sel_hi:[1,0]
	v_exp_f32_e32 v17, v22
	s_and_b64 vcc, exec, s[4:5]
	v_fma_f32 v17, v17, v239, v239
	v_rcp_f32_e32 v22, v17
	v_exp_f32_e32 v17, v23
	s_nop 0
	v_fma_f32 v17, v17, v239, v239
	v_rcp_f32_e32 v23, v17
	v_exp_f32_e32 v17, v20
	s_nop 0
	v_fma_f32 v17, v17, v239, v239
	v_rcp_f32_e32 v20, v17
	v_exp_f32_e32 v17, v21
	v_pk_mul_f32 v[8:9], v[8:9], v[22:23]
	v_fma_f32 v17, v17, v239, v239
	v_rcp_f32_e32 v21, v17
	v_cvt_pk_bf16_f32 v8, v8, v9
	s_nop 0
	v_pk_mul_f32 v[10:11], v[10:11], v[20:21]
	s_nop 0
	v_cvt_pk_bf16_f32 v9, v10, v11
	v_pk_mul_f32 v[12:13], v[4:5], v[16:17] op_sel_hi:[1,0]
	v_pk_mul_f32 v[10:11], v[6:7], v[16:17] op_sel_hi:[1,0]
	v_exp_f32_e32 v12, v12
	v_exp_f32_e32 v13, v13
	v_exp_f32_e32 v10, v10
	v_exp_f32_e32 v11, v11
	v_fma_f32 v12, v12, v239, v239
	v_fma_f32 v13, v13, v239, v239
	v_rcp_f32_e32 v12, v12
	v_rcp_f32_e32 v13, v13
	v_fma_f32 v10, v10, v239, v239
	v_fma_f32 v11, v11, v239, v239
	v_rcp_f32_e32 v10, v10
	v_rcp_f32_e32 v11, v11
	s_nop 0
	v_pk_mul_f32 v[0:1], v[0:1], v[12:13]
	s_nop 0
	v_pk_mul_f32 v[2:3], v[2:3], v[10:11]
	v_cvt_pk_bf16_f32 v10, v0, v1
	v_mad_i64_i32 v[0:1], s[0:1], v64, s9, v[112:113]
	v_cvt_pk_bf16_f32 v11, v2, v3
	v_lshl_add_u64 v[0:1], v[0:1], 0, v[114:115]
	s_mov_b32 s0, s10
	global_store_dwordx4 v[0:1], v[8:11], off
	s_cbranch_vccz .LBB0_399
	s_waitcnt vmcnt(0)
	s_cmpk_gt_u32 s25, 0xff
	s_cbranch_scc1 .LBB0_406
	s_barrier

.LBB0_2804:
	s_add_u32 s20, s18, 0xfffc0080
	s_addc_u32 s21, s19, -1
	s_add_i32 s42, 0, 0x10000
	ds_read_b128 v[138:141], v202
	ds_read_b128 v[142:145], v202 offset:1024
	ds_read_b128 v[146:149], v202 offset:2048
	ds_read_b128 v[154:157], v202 offset:3072
	s_cmp_eq_u32 s41, 12
	s_cselect_b32 s23, s9, s21
	s_cselect_b32 s22, s33, s20
	s_cselect_b32 s21, s11, s40
	s_cselect_b32 s20, s38, s39
	s_add_i32 m0, s17, 0xc000
	ds_read_b128 v[158:161], v152
	ds_read_b128 v[162:165], v152 offset:1024
	ds_read_b128 v[166:169], v152 offset:2048
	ds_read_b128 v[170:173], v152 offset:3072
	ds_read_b128 v[174:177], v152 offset:4096
	ds_read_b128 v[178:181], v152 offset:5120
	ds_read_b128 v[182:185], v152 offset:6144
	ds_read_b128 v[186:189], v152 offset:7168
	global_load_lds_dwordx4 v136, s[18:19]
	s_add_i32 m0, s17, 0xe000
	s_nop 0
	global_load_lds_dwordx4 v134, s[18:19]
	s_waitcnt lgkmcnt(8)
	s_barrier
	s_waitcnt lgkmcnt(0)
	v_mfma_f32_16x16x32_bf16 v[124:127], v[138:141], v[158:161], v[124:127]
	v_mfma_f32_16x16x32_bf16 v[116:119], v[146:149], v[158:161], v[116:119]
	v_mfma_f32_16x16x32_bf16 v[108:111], v[138:141], v[166:169], v[108:111]
	v_mfma_f32_16x16x32_bf16 v[100:103], v[146:149], v[166:169], v[100:103]
	v_mfma_f32_16x16x32_bf16 v[92:95], v[138:141], v[174:177], v[92:95]
	v_mfma_f32_16x16x32_bf16 v[84:87], v[146:149], v[174:177], v[84:87]
	v_mfma_f32_16x16x32_bf16 v[76:79], v[138:141], v[182:185], v[76:79]
	v_mfma_f32_16x16x32_bf16 v[68:71], v[146:149], v[182:185], v[68:71]
	v_mfma_f32_16x16x32_bf16 v[124:127], v[142:145], v[162:165], v[124:127]
	v_mfma_f32_16x16x32_bf16 v[116:119], v[154:157], v[162:165], v[116:119]
	v_mfma_f32_16x16x32_bf16 v[108:111], v[142:145], v[170:173], v[108:111]
	v_mfma_f32_16x16x32_bf16 v[100:103], v[154:157], v[170:173], v[100:103]
	v_mfma_f32_16x16x32_bf16 v[92:95], v[142:145], v[178:181], v[92:95]
	v_mfma_f32_16x16x32_bf16 v[84:87], v[154:157], v[178:181], v[84:87]
	v_mfma_f32_16x16x32_bf16 v[76:79], v[142:145], v[186:189], v[76:79]
	v_mfma_f32_16x16x32_bf16 v[68:71], v[154:157], v[186:189], v[68:71]
	s_barrier
	s_add_i32 s44, 0, 0x14000
	s_add_i32 s42, s42, s28
	s_mov_b32 m0, s42
	ds_read_b128 v[198:201], v203
	ds_read_b128 v[206:209], v203 offset:1024
	ds_read_b128 v[210:213], v203 offset:2048
	ds_read_b128 v[214:217], v203 offset:3072
	global_load_lds_dwordx4 v192, s[20:21]
	s_add_i32 m0, s42, 0x2000
	s_nop 0
	global_load_lds_dwordx4 v128, s[20:21]
	s_barrier
	s_waitcnt lgkmcnt(0)
	v_mfma_f32_16x16x32_bf16 v[120:123], v[198:201], v[158:161], v[120:123]
	v_mfma_f32_16x16x32_bf16 v[112:115], v[210:213], v[158:161], v[112:115]
	v_mfma_f32_16x16x32_bf16 v[104:107], v[198:201], v[166:169], v[104:107]
	v_mfma_f32_16x16x32_bf16 v[96:99], v[210:213], v[166:169], v[96:99]
	v_mfma_f32_16x16x32_bf16 v[88:91], v[198:201], v[174:177], v[88:91]
	v_mfma_f32_16x16x32_bf16 v[80:83], v[210:213], v[174:177], v[80:83]
	v_mfma_f32_16x16x32_bf16 v[72:75], v[198:201], v[182:185], v[72:75]
	v_mfma_f32_16x16x32_bf16 v[64:67], v[210:213], v[182:185], v[64:67]
	v_mfma_f32_16x16x32_bf16 v[120:123], v[206:209], v[162:165], v[120:123]
	v_mfma_f32_16x16x32_bf16 v[112:115], v[214:217], v[162:165], v[112:115]
	v_mfma_f32_16x16x32_bf16 v[104:107], v[206:209], v[170:173], v[104:107]
	v_mfma_f32_16x16x32_bf16 v[96:99], v[214:217], v[170:173], v[96:99]
	v_mfma_f32_16x16x32_bf16 v[88:91], v[206:209], v[178:181], v[88:91]
	v_mfma_f32_16x16x32_bf16 v[80:83], v[214:217], v[178:181], v[80:83]
	v_mfma_f32_16x16x32_bf16 v[72:75], v[206:209], v[186:189], v[72:75]
	v_mfma_f32_16x16x32_bf16 v[64:67], v[214:217], v[186:189], v[64:67]
	s_mov_b32 m0, s17
	s_add_u32 vcc_lo, s22, 0x80
	s_addc_u32 vcc_hi, s23, 0
	s_barrier
	ds_read_b128 v[158:161], v152 offset:16384
	ds_read_b128 v[162:165], v152 offset:17408
	ds_read_b128 v[166:169], v152 offset:18432
	ds_read_b128 v[170:173], v152 offset:19456
	ds_read_b128 v[174:177], v152 offset:20480
	ds_read_b128 v[178:181], v152 offset:21504
	ds_read_b128 v[182:185], v152 offset:22528
	ds_read_b128 v[186:189], v152 offset:23552
	global_load_lds_dwordx4 v132, s[22:23]
	s_mov_b32 m0, s29
	s_nop 0
	global_load_lds_dwordx4 v130, s[22:23]
	s_barrier
	s_waitcnt lgkmcnt(0)
	v_mfma_f32_16x16x32_bf16 v[60:63], v[138:141], v[158:161], v[60:63]
	v_mfma_f32_16x16x32_bf16 v[52:55], v[146:149], v[158:161], v[52:55]
	v_mfma_f32_16x16x32_bf16 v[44:47], v[138:141], v[166:169], v[44:47]
	v_mfma_f32_16x16x32_bf16 v[36:39], v[146:149], v[166:169], v[36:39]
	v_mfma_f32_16x16x32_bf16 v[28:31], v[138:141], v[174:177], v[28:31]
	v_mfma_f32_16x16x32_bf16 v[20:23], v[146:149], v[174:177], v[20:23]
	v_mfma_f32_16x16x32_bf16 v[12:15], v[138:141], v[182:185], v[12:15]
	v_mfma_f32_16x16x32_bf16 v[4:7], v[146:149], v[182:185], v[4:7]
	v_mfma_f32_16x16x32_bf16 v[60:63], v[142:145], v[162:165], v[60:63]
	v_mfma_f32_16x16x32_bf16 v[52:55], v[154:157], v[162:165], v[52:55]
	v_mfma_f32_16x16x32_bf16 v[44:47], v[142:145], v[170:173], v[44:47]
	v_mfma_f32_16x16x32_bf16 v[36:39], v[154:157], v[170:173], v[36:39]
	v_mfma_f32_16x16x32_bf16 v[28:31], v[142:145], v[178:181], v[28:31]
	v_mfma_f32_16x16x32_bf16 v[20:23], v[154:157], v[178:181], v[20:23]
	v_mfma_f32_16x16x32_bf16 v[12:15], v[142:145], v[186:189], v[12:15]
	v_mfma_f32_16x16x32_bf16 v[4:7], v[154:157], v[186:189], v[4:7]
	s_barrier
	s_add_u32 s42, s20, 0x40000
	s_addc_u32 s43, s21, 0
	s_add_i32 s44, s44, s28
	s_mov_b32 m0, s44
	s_nop 0
	global_load_lds_dwordx4 v192, s[42:43]
	s_add_i32 m0, s44, 0x2000
	s_nop 0
	global_load_lds_dwordx4 v128, s[42:43]
	s_waitcnt vmcnt(6)
	s_barrier
	v_mfma_f32_16x16x32_bf16 v[56:59], v[198:201], v[158:161], v[56:59]
	v_mfma_f32_16x16x32_bf16 v[48:51], v[210:213], v[158:161], v[48:51]
	v_mfma_f32_16x16x32_bf16 v[40:43], v[198:201], v[166:169], v[40:43]
	v_mfma_f32_16x16x32_bf16 v[32:35], v[210:213], v[166:169], v[32:35]
	v_mfma_f32_16x16x32_bf16 v[24:27], v[198:201], v[174:177], v[24:27]
	v_mfma_f32_16x16x32_bf16 v[16:19], v[210:213], v[174:177], v[16:19]
	v_mfma_f32_16x16x32_bf16 v[8:11], v[198:201], v[182:185], v[8:11]
	v_mfma_f32_16x16x32_bf16 v[0:3], v[210:213], v[182:185], v[0:3]
	v_mfma_f32_16x16x32_bf16 v[56:59], v[206:209], v[162:165], v[56:59]
	v_mfma_f32_16x16x32_bf16 v[48:51], v[214:217], v[162:165], v[48:51]
	v_mfma_f32_16x16x32_bf16 v[40:43], v[206:209], v[170:173], v[40:43]
	v_mfma_f32_16x16x32_bf16 v[32:35], v[214:217], v[170:173], v[32:35]
	v_mfma_f32_16x16x32_bf16 v[24:27], v[206:209], v[178:181], v[24:27]
	v_mfma_f32_16x16x32_bf16 v[16:19], v[214:217], v[178:181], v[16:19]
	v_mfma_f32_16x16x32_bf16 v[8:11], v[206:209], v[186:189], v[8:11]
	v_mfma_f32_16x16x32_bf16 v[0:3], v[214:217], v[186:189], v[0:3]
	s_add_i32 s42, 0, 0x18000
	s_barrier
	ds_read_b128 v[138:141], v204
	ds_read_b128 v[142:145], v204 offset:1024
	ds_read_b128 v[146:149], v204 offset:2048
	ds_read_b128 v[154:157], v204 offset:3072
	s_add_u32 s22, s22, 0x40000
	s_addc_u32 s23, s23, 0
	s_mov_b32 m0, s30
	ds_read_b128 v[158:161], v152 offset:32768
	ds_read_b128 v[162:165], v152 offset:33792
	ds_read_b128 v[166:169], v152 offset:34816
	ds_read_b128 v[170:173], v152 offset:35840
	ds_read_b128 v[174:177], v152 offset:36864
	ds_read_b128 v[178:181], v152 offset:37888
	ds_read_b128 v[182:185], v152 offset:38912
	ds_read_b128 v[186:189], v152 offset:39936
	global_load_lds_dwordx4 v132, s[22:23]
	s_mov_b32 m0, s31
	s_nop 0
	global_load_lds_dwordx4 v130, s[22:23]
	s_waitcnt lgkmcnt(8)
	s_barrier
	s_waitcnt lgkmcnt(0)
	v_mfma_f32_16x16x32_bf16 v[124:127], v[138:141], v[158:161], v[124:127]
	v_mfma_f32_16x16x32_bf16 v[116:119], v[146:149], v[158:161], v[116:119]
	v_mfma_f32_16x16x32_bf16 v[108:111], v[138:141], v[166:169], v[108:111]
	v_mfma_f32_16x16x32_bf16 v[100:103], v[146:149], v[166:169], v[100:103]
	v_mfma_f32_16x16x32_bf16 v[92:95], v[138:141], v[174:177], v[92:95]
	v_mfma_f32_16x16x32_bf16 v[84:87], v[146:149], v[174:177], v[84:87]
	v_mfma_f32_16x16x32_bf16 v[76:79], v[138:141], v[182:185], v[76:79]
	v_mfma_f32_16x16x32_bf16 v[68:71], v[146:149], v[182:185], v[68:71]
	v_mfma_f32_16x16x32_bf16 v[124:127], v[142:145], v[162:165], v[124:127]
	v_mfma_f32_16x16x32_bf16 v[116:119], v[154:157], v[162:165], v[116:119]
	v_mfma_f32_16x16x32_bf16 v[108:111], v[142:145], v[170:173], v[108:111]
	v_mfma_f32_16x16x32_bf16 v[100:103], v[154:157], v[170:173], v[100:103]
	v_mfma_f32_16x16x32_bf16 v[92:95], v[142:145], v[178:181], v[92:95]
	v_mfma_f32_16x16x32_bf16 v[84:87], v[154:157], v[178:181], v[84:87]
	v_mfma_f32_16x16x32_bf16 v[76:79], v[142:145], v[186:189], v[76:79]
	v_mfma_f32_16x16x32_bf16 v[68:71], v[154:157], v[186:189], v[68:71]
	s_barrier
	s_add_i32 s22, 0, 0x1c000
	s_add_i32 s23, s42, s28
	s_add_u32 s100, s20, 0x80
	s_addc_u32 s101, s21, 0
	s_mov_b32 m0, s23
	ds_read_b128 v[198:201], v205
	ds_read_b128 v[206:209], v205 offset:1024
	ds_read_b128 v[210:213], v205 offset:2048
	ds_read_b128 v[214:217], v205 offset:3072
	global_load_lds_dwordx4 v192, s[100:101]
	s_add_i32 m0, s23, 0x2000
	s_nop 0
	global_load_lds_dwordx4 v128, s[100:101]
	s_barrier
	s_waitcnt lgkmcnt(0)
	v_mfma_f32_16x16x32_bf16 v[120:123], v[198:201], v[158:161], v[120:123]
	v_mfma_f32_16x16x32_bf16 v[112:115], v[210:213], v[158:161], v[112:115]
	v_mfma_f32_16x16x32_bf16 v[104:107], v[198:201], v[166:169], v[104:107]
	v_mfma_f32_16x16x32_bf16 v[96:99], v[210:213], v[166:169], v[96:99]
	v_mfma_f32_16x16x32_bf16 v[88:91], v[198:201], v[174:177], v[88:91]
	v_mfma_f32_16x16x32_bf16 v[80:83], v[210:213], v[174:177], v[80:83]
	v_mfma_f32_16x16x32_bf16 v[72:75], v[198:201], v[182:185], v[72:75]
	v_mfma_f32_16x16x32_bf16 v[64:67], v[210:213], v[182:185], v[64:67]
	v_mfma_f32_16x16x32_bf16 v[120:123], v[206:209], v[162:165], v[120:123]
	v_mfma_f32_16x16x32_bf16 v[112:115], v[214:217], v[162:165], v[112:115]
	v_mfma_f32_16x16x32_bf16 v[104:107], v[206:209], v[170:173], v[104:107]
	v_mfma_f32_16x16x32_bf16 v[96:99], v[214:217], v[170:173], v[96:99]
	v_mfma_f32_16x16x32_bf16 v[88:91], v[206:209], v[178:181], v[88:91]
	v_mfma_f32_16x16x32_bf16 v[80:83], v[214:217], v[178:181], v[80:83]
	v_mfma_f32_16x16x32_bf16 v[72:75], v[206:209], v[186:189], v[72:75]
	v_mfma_f32_16x16x32_bf16 v[64:67], v[214:217], v[186:189], v[64:67]
	s_mov_b32 m0, s34
	s_barrier
	ds_read_b128 v[158:161], v152 offset:49152
	ds_read_b128 v[162:165], v152 offset:50176
	ds_read_b128 v[166:169], v152 offset:51200
	ds_read_b128 v[170:173], v152 offset:52224
	ds_read_b128 v[174:177], v152 offset:53248
	ds_read_b128 v[178:181], v152 offset:54272
	ds_read_b128 v[182:185], v152 offset:55296
	ds_read_b128 v[186:189], v152 offset:56320
	global_load_lds_dwordx4 v132, vcc
	s_mov_b32 m0, s35
	s_nop 0
	global_load_lds_dwordx4 v130, vcc
	s_barrier
	s_waitcnt lgkmcnt(0)
	v_mfma_f32_16x16x32_bf16 v[60:63], v[138:141], v[158:161], v[60:63]
	v_mfma_f32_16x16x32_bf16 v[52:55], v[146:149], v[158:161], v[52:55]
	v_mfma_f32_16x16x32_bf16 v[44:47], v[138:141], v[166:169], v[44:47]
	v_mfma_f32_16x16x32_bf16 v[36:39], v[146:149], v[166:169], v[36:39]
	v_mfma_f32_16x16x32_bf16 v[28:31], v[138:141], v[174:177], v[28:31]
	v_mfma_f32_16x16x32_bf16 v[20:23], v[146:149], v[174:177], v[20:23]
	v_mfma_f32_16x16x32_bf16 v[12:15], v[138:141], v[182:185], v[12:15]
	v_mfma_f32_16x16x32_bf16 v[4:7], v[146:149], v[182:185], v[4:7]
	v_mfma_f32_16x16x32_bf16 v[60:63], v[142:145], v[162:165], v[60:63]
	v_mfma_f32_16x16x32_bf16 v[52:55], v[154:157], v[162:165], v[52:55]
	v_mfma_f32_16x16x32_bf16 v[44:47], v[142:145], v[170:173], v[44:47]
	v_mfma_f32_16x16x32_bf16 v[36:39], v[154:157], v[170:173], v[36:39]
	v_mfma_f32_16x16x32_bf16 v[28:31], v[142:145], v[178:181], v[28:31]
	v_mfma_f32_16x16x32_bf16 v[20:23], v[154:157], v[178:181], v[20:23]
	v_mfma_f32_16x16x32_bf16 v[12:15], v[142:145], v[186:189], v[12:15]
	v_mfma_f32_16x16x32_bf16 v[4:7], v[154:157], v[186:189], v[4:7]
	s_barrier
	s_add_u32 s20, s20, 0x40080
	s_addc_u32 s21, s21, 0
	s_add_i32 s22, s22, s28
	s_mov_b32 m0, s22
	s_nop 0
	global_load_lds_dwordx4 v192, s[20:21]
	s_add_i32 m0, s22, 0x2000
	s_nop 0
	global_load_lds_dwordx4 v128, s[20:21]
	s_waitcnt vmcnt(6)
	s_barrier
	v_mfma_f32_16x16x32_bf16 v[56:59], v[198:201], v[158:161], v[56:59]
	v_mfma_f32_16x16x32_bf16 v[48:51], v[210:213], v[158:161], v[48:51]
	v_mfma_f32_16x16x32_bf16 v[40:43], v[198:201], v[166:169], v[40:43]
	v_mfma_f32_16x16x32_bf16 v[32:35], v[210:213], v[166:169], v[32:35]
	v_mfma_f32_16x16x32_bf16 v[24:27], v[198:201], v[174:177], v[24:27]
	v_mfma_f32_16x16x32_bf16 v[16:19], v[210:213], v[174:177], v[16:19]
	v_mfma_f32_16x16x32_bf16 v[8:11], v[198:201], v[182:185], v[8:11]
	v_mfma_f32_16x16x32_bf16 v[0:3], v[210:213], v[182:185], v[0:3]
	v_mfma_f32_16x16x32_bf16 v[56:59], v[206:209], v[162:165], v[56:59]
	v_mfma_f32_16x16x32_bf16 v[48:51], v[214:217], v[162:165], v[48:51]
	v_mfma_f32_16x16x32_bf16 v[40:43], v[206:209], v[170:173], v[40:43]
	v_mfma_f32_16x16x32_bf16 v[32:35], v[214:217], v[170:173], v[32:35]
	v_mfma_f32_16x16x32_bf16 v[24:27], v[206:209], v[178:181], v[24:27]
	v_mfma_f32_16x16x32_bf16 v[16:19], v[214:217], v[178:181], v[16:19]
	v_mfma_f32_16x16x32_bf16 v[8:11], v[206:209], v[186:189], v[8:11]
	v_mfma_f32_16x16x32_bf16 v[0:3], v[214:217], v[186:189], v[0:3]
	s_add_i32 s41, s41, 2
	s_add_u32 s39, s39, 0x100
	s_addc_u32 s40, s40, 0
	s_add_u32 s18, s18, 0x100
	s_addc_u32 s19, s19, 0
	s_cmp_gt_u32 s41, 13
	s_barrier
	s_cbranch_scc0 .LBB0_2804
	v_mov_b32_e32 v139, v252
	s_lshl_b32 s11, s16, 8
	v_readfirstlane_b32 s9, v139
	s_ashr_i32 s16, s9, 2
	s_andn2_b32 s16, s16, 63
	s_lshr_b32 s9, s9, 1
	s_add_i32 s16, s16, s11
	s_lshl_b32 s11, s37, 7
	s_and_b32 s9, s9, 0x60
	v_and_or_b32 v138, v139, 15, s16
	s_or_b32 s9, s9, s11
	v_lshrrev_b32_e32 v139, 1, v139
	v_and_or_b32 v148, v139, 24, s9
	v_ashrrev_i32_e32 v139, 31, v138
	v_lshl_add_u64 v[140:141], v[138:139], 2, s[6:7]
	v_or_b32_e32 v146, 16, v138
	v_ashrrev_i32_e32 v147, 31, v146
	v_lshl_add_u64 v[142:143], v[146:147], 2, s[6:7]
	v_or_b32_e32 v144, 32, v138
	v_ashrrev_i32_e32 v145, 31, v144
	v_lshl_add_u64 v[142:143], v[144:145], 2, s[6:7]
	v_or_b32_e32 v142, 48, v138
	v_ashrrev_i32_e32 v143, 31, v142
	v_lshl_add_u64 v[154:155], v[142:143], 2, s[6:7]
	v_pk_mul_f32 v[120:121], v[124:125], v[120:121]
	v_pk_mul_f32 v[122:123], v[126:127], v[122:123]
	v_pk_mul_f32 v[112:113], v[116:117], v[112:113]
	v_pk_mul_f32 v[114:115], v[118:119], v[114:115]
	v_ashrrev_i32_e32 v149, 31, v148
	s_movk_i32 s9, 0x1600
	v_pk_mul_f32 v[104:105], v[108:109], v[104:105]
	v_pk_mul_f32 v[106:107], v[110:111], v[106:107]
	v_pk_mul_f32 v[96:97], v[100:101], v[96:97]
	v_pk_mul_f32 v[98:99], v[102:103], v[98:99]
	v_pk_mul_f32 v[88:89], v[92:93], v[88:89]
	v_pk_mul_f32 v[90:91], v[94:95], v[90:91]
	v_pk_mul_f32 v[80:81], v[84:85], v[80:81]
	v_pk_mul_f32 v[82:83], v[86:87], v[82:83]
	v_pk_mul_f32 v[72:73], v[76:77], v[72:73]
	v_pk_mul_f32 v[74:75], v[78:79], v[74:75]
	v_pk_mul_f32 v[64:65], v[68:69], v[64:65]
	v_pk_mul_f32 v[66:67], v[70:71], v[66:67]
	v_pk_mul_f32 v[56:57], v[60:61], v[56:57]
	v_pk_mul_f32 v[58:59], v[62:63], v[58:59]
	v_pk_mul_f32 v[48:49], v[52:53], v[48:49]
	v_pk_mul_f32 v[50:51], v[54:55], v[50:51]
	v_pk_mul_f32 v[40:41], v[44:45], v[40:41]
	v_pk_mul_f32 v[42:43], v[46:47], v[42:43]
	v_pk_mul_f32 v[32:33], v[36:37], v[32:33]
	v_pk_mul_f32 v[34:35], v[38:39], v[34:35]
	v_pk_mul_f32 v[24:25], v[28:29], v[24:25]
	v_pk_mul_f32 v[26:27], v[30:31], v[26:27]
	v_pk_mul_f32 v[16:17], v[20:21], v[16:17]
	v_pk_mul_f32 v[18:19], v[22:23], v[18:19]
	v_pk_mul_f32 v[8:9], v[12:13], v[8:9]
	v_pk_mul_f32 v[10:11], v[14:15], v[10:11]
	v_pk_mul_f32 v[0:1], v[4:5], v[0:1]
	v_pk_mul_f32 v[2:3], v[6:7], v[2:3]
	s_mov_b32 s37, s10
	s_mov_b32 s16, s8
	s_mov_b64 s[20:21], s[12:13]
	v_fmamk_f32 v239, v231, 0x3a800000, v194
	s_nop 0
	v_rsq_f32_e32 v143, v239
	s_nop 0
	v_mul_f32_e32 v154, 0xbfb8aa3b, v143
	v_pk_mul_f32 v[158:159], v[124:125], v[154:155] op_sel_hi:[1,0]
	s_nop 0
	v_exp_f32_e32 v143, v158
	v_pk_mul_f32 v[156:157], v[126:127], v[154:155] op_sel_hi:[1,0]
	v_fma_f32 v143, v143, v239, v239
	v_rcp_f32_e32 v158, v143
	v_exp_f32_e32 v143, v159
	s_nop 0
	v_fma_f32 v143, v143, v239, v239
	v_rcp_f32_e32 v159, v143
	v_exp_f32_e32 v143, v156
	s_nop 0
	v_fma_f32 v143, v143, v239, v239
	v_rcp_f32_e32 v156, v143
	v_exp_f32_e32 v143, v157
	v_pk_mul_f32 v[120:121], v[120:121], v[158:159]
	v_fma_f32 v143, v143, v239, v239
	v_rcp_f32_e32 v157, v143
	v_cvt_pk_bf16_f32 v120, v120, v121
	s_nop 0
	v_pk_mul_f32 v[122:123], v[122:123], v[156:157]
	s_nop 0
	v_cvt_pk_bf16_f32 v121, v122, v123
	v_pk_mul_f32 v[124:125], v[116:117], v[154:155] op_sel_hi:[1,0]
	v_pk_mul_f32 v[122:123], v[118:119], v[154:155] op_sel_hi:[1,0]
	v_exp_f32_e32 v124, v124
	v_exp_f32_e32 v125, v125
	v_exp_f32_e32 v122, v122
	v_exp_f32_e32 v123, v123
	v_fma_f32 v124, v124, v239, v239
	v_fma_f32 v125, v125, v239, v239
	v_rcp_f32_e32 v124, v124
	v_rcp_f32_e32 v125, v125
	v_fma_f32 v122, v122, v239, v239
	v_fma_f32 v123, v123, v239, v239
	v_rcp_f32_e32 v122, v122
	v_rcp_f32_e32 v123, v123
	s_nop 0
	v_pk_mul_f32 v[112:113], v[112:113], v[124:125]
	s_nop 0
	v_pk_mul_f32 v[114:115], v[114:115], v[122:123]
	v_cvt_pk_bf16_f32 v122, v112, v113
	v_mov_b64_e32 v[112:113], s[4:5]
	v_cvt_pk_bf16_f32 v123, v114, v115
	v_mad_i64_i32 v[116:117], s[18:19], v138, s9, v[112:113]
	v_lshlrev_b64 v[114:115], 1, v[148:149]
	v_lshl_add_u64 v[116:117], v[116:117], 0, v[114:115]
	global_store_dwordx4 v[116:117], v[120:123], off
	v_fmamk_f32 v239, v232, 0x3a800000, v194
	s_nop 0
	v_rsq_f32_e32 v116, v239
	s_nop 0
	v_mul_f32_e32 v118, 0xbfb8aa3b, v116
	v_pk_mul_f32 v[122:123], v[108:109], v[118:119] op_sel_hi:[1,0]
	v_pk_mul_f32 v[120:121], v[110:111], v[118:119] op_sel_hi:[1,0]
	v_exp_f32_e32 v117, v122
	s_nop 0
	v_fma_f32 v117, v117, v239, v239
	v_rcp_f32_e32 v122, v117
	v_exp_f32_e32 v117, v123
	s_nop 0
	v_fma_f32 v117, v117, v239, v239
	v_rcp_f32_e32 v123, v117
	v_exp_f32_e32 v117, v120
	s_nop 0
	v_fma_f32 v117, v117, v239, v239
	v_rcp_f32_e32 v120, v117
	v_exp_f32_e32 v117, v121
	s_nop 0
	v_fma_f32 v117, v117, v239, v239
	v_rcp_f32_e32 v121, v117
	s_nop 0
	v_pk_mul_f32 v[104:105], v[104:105], v[122:123]
	s_nop 0
	v_pk_mul_f32 v[106:107], v[106:107], v[120:121]
	v_cvt_pk_bf16_f32 v104, v104, v105
	v_cvt_pk_bf16_f32 v105, v106, v107
	v_pk_mul_f32 v[108:109], v[100:101], v[118:119] op_sel_hi:[1,0]
	v_pk_mul_f32 v[106:107], v[102:103], v[118:119] op_sel_hi:[1,0]
	v_exp_f32_e32 v108, v108
	v_exp_f32_e32 v109, v109
	v_exp_f32_e32 v106, v106
	v_exp_f32_e32 v107, v107
	v_fma_f32 v108, v108, v239, v239
	v_fma_f32 v109, v109, v239, v239
	v_rcp_f32_e32 v108, v108
	v_rcp_f32_e32 v109, v109
	v_fma_f32 v106, v106, v239, v239
	v_fma_f32 v107, v107, v239, v239
	v_rcp_f32_e32 v106, v106
	v_rcp_f32_e32 v107, v107
	s_nop 0
	v_pk_mul_f32 v[96:97], v[96:97], v[108:109]
	s_nop 0
	v_pk_mul_f32 v[98:99], v[98:99], v[106:107]
	v_cvt_pk_bf16_f32 v106, v96, v97
	v_mad_i64_i32 v[96:97], s[18:19], v146, s9, v[112:113]
	v_cvt_pk_bf16_f32 v107, v98, v99
	v_lshl_add_u64 v[96:97], v[96:97], 0, v[114:115]
	global_store_dwordx4 v[96:97], v[104:107], off
	v_fmamk_f32 v239, v233, 0x3a800000, v194
	s_nop 0
	v_rsq_f32_e32 v96, v239
	s_nop 0
	v_mov_b32_e32 v97, v96
	v_mul_f32_e32 v96, 0xbfb8aa3b, v97
	v_pk_mul_f32 v[102:103], v[92:93], v[96:97] op_sel_hi:[1,0]
	s_nop 0
	v_pk_mul_f32 v[100:101], v[94:95], v[96:97] op_sel_hi:[1,0]
	v_exp_f32_e32 v97, v102
	s_nop 0
	v_fma_f32 v97, v97, v239, v239
	v_rcp_f32_e32 v102, v97
	v_exp_f32_e32 v97, v103
	s_nop 0
	v_fma_f32 v97, v97, v239, v239
	v_rcp_f32_e32 v103, v97
	v_exp_f32_e32 v97, v100
	s_nop 0
	v_fma_f32 v97, v97, v239, v239
	v_rcp_f32_e32 v100, v97
	v_exp_f32_e32 v97, v101
	v_pk_mul_f32 v[88:89], v[88:89], v[102:103]
	v_fma_f32 v97, v97, v239, v239
	v_rcp_f32_e32 v101, v97
	v_cvt_pk_bf16_f32 v88, v88, v89
	s_nop 0
	v_pk_mul_f32 v[90:91], v[90:91], v[100:101]
	s_nop 0
	v_cvt_pk_bf16_f32 v89, v90, v91
	v_pk_mul_f32 v[92:93], v[84:85], v[96:97] op_sel_hi:[1,0]
	v_pk_mul_f32 v[90:91], v[86:87], v[96:97] op_sel_hi:[1,0]
	v_exp_f32_e32 v92, v92
	v_exp_f32_e32 v93, v93
	v_exp_f32_e32 v90, v90
	v_exp_f32_e32 v91, v91
	v_fma_f32 v92, v92, v239, v239
	v_fma_f32 v93, v93, v239, v239
	v_rcp_f32_e32 v92, v92
	v_rcp_f32_e32 v93, v93
	v_fma_f32 v90, v90, v239, v239
	v_fma_f32 v91, v91, v239, v239
	v_rcp_f32_e32 v90, v90
	v_rcp_f32_e32 v91, v91
	s_nop 0
	v_pk_mul_f32 v[80:81], v[80:81], v[92:93]
	s_nop 0
	v_pk_mul_f32 v[82:83], v[82:83], v[90:91]
	v_cvt_pk_bf16_f32 v90, v80, v81
	v_mad_i64_i32 v[80:81], s[18:19], v144, s9, v[112:113]
	v_cvt_pk_bf16_f32 v91, v82, v83
	v_lshl_add_u64 v[80:81], v[80:81], 0, v[114:115]
	global_store_dwordx4 v[80:81], v[88:91], off
	v_fmamk_f32 v239, v234, 0x3a800000, v194
	s_nop 0
	v_rsq_f32_e32 v80, v239
	s_nop 0
	v_mov_b32_e32 v81, v80
	v_mul_f32_e32 v80, 0xbfb8aa3b, v81
	v_pk_mul_f32 v[86:87], v[76:77], v[80:81] op_sel_hi:[1,0]
	s_nop 0
	v_pk_mul_f32 v[84:85], v[78:79], v[80:81] op_sel_hi:[1,0]
	v_exp_f32_e32 v81, v86
	s_nop 0
	v_fma_f32 v81, v81, v239, v239
	v_rcp_f32_e32 v86, v81
	v_exp_f32_e32 v81, v87
	s_nop 0
	v_fma_f32 v81, v81, v239, v239
	v_rcp_f32_e32 v87, v81
	v_exp_f32_e32 v81, v84
	s_nop 0
	v_fma_f32 v81, v81, v239, v239
	v_rcp_f32_e32 v84, v81
	v_exp_f32_e32 v81, v85
	v_pk_mul_f32 v[72:73], v[72:73], v[86:87]
	v_fma_f32 v81, v81, v239, v239
	v_rcp_f32_e32 v85, v81
	v_cvt_pk_bf16_f32 v72, v72, v73
	s_nop 0
	v_pk_mul_f32 v[74:75], v[74:75], v[84:85]
	s_nop 0
	v_cvt_pk_bf16_f32 v73, v74, v75
	v_pk_mul_f32 v[76:77], v[68:69], v[80:81] op_sel_hi:[1,0]
	v_pk_mul_f32 v[74:75], v[70:71], v[80:81] op_sel_hi:[1,0]
	v_exp_f32_e32 v76, v76
	v_exp_f32_e32 v77, v77
	v_exp_f32_e32 v74, v74
	v_exp_f32_e32 v75, v75
	v_fma_f32 v76, v76, v239, v239
	v_fma_f32 v77, v77, v239, v239
	v_rcp_f32_e32 v76, v76
	v_rcp_f32_e32 v77, v77
	v_fma_f32 v74, v74, v239, v239
	v_fma_f32 v75, v75, v239, v239
	v_rcp_f32_e32 v74, v74
	v_rcp_f32_e32 v75, v75
	s_nop 0
	v_pk_mul_f32 v[64:65], v[64:65], v[76:77]
	v_add_u32_e32 v69, 0x90, v138
	s_nop 0
	v_pk_mul_f32 v[66:67], v[66:67], v[74:75]
	v_cvt_pk_bf16_f32 v74, v64, v65
	v_mad_i64_i32 v[64:65], s[18:19], v142, s9, v[112:113]
	v_cvt_pk_bf16_f32 v75, v66, v67
	v_lshl_add_u64 v[64:65], v[64:65], 0, v[114:115]
	global_store_dwordx4 v[64:65], v[72:75], off
	v_add_u32_e32 v67, 0x80, v138
	v_add_u32_e32 v66, 0xa0, v138
	v_add_u32_e32 v64, 0xb0, v138
	v_fmamk_f32 v239, v235, 0x3a800000, v194
	s_nop 0
	v_rsq_f32_e32 v68, v239
	s_nop 0
	v_mov_b32_e32 v70, v68
	v_mul_f32_e32 v68, 0xbfb8aa3b, v70
	v_pk_mul_f32 v[74:75], v[60:61], v[68:69] op_sel_hi:[1,0]
	v_pk_mul_f32 v[72:73], v[62:63], v[68:69] op_sel_hi:[1,0]
	v_exp_f32_e32 v74, v74
	v_exp_f32_e32 v75, v75
	v_exp_f32_e32 v72, v72
	v_exp_f32_e32 v73, v73
	v_fma_f32 v74, v74, v239, v239
	v_fma_f32 v75, v75, v239, v239
	v_rcp_f32_e32 v74, v74
	v_rcp_f32_e32 v75, v75
	v_fma_f32 v72, v72, v239, v239
	v_fma_f32 v73, v73, v239, v239
	v_rcp_f32_e32 v72, v72
	v_rcp_f32_e32 v73, v73
	s_nop 0
	s_nop 0
	v_pk_mul_f32 v[56:57], v[56:57], v[74:75]
	s_nop 0
	v_pk_mul_f32 v[58:59], v[58:59], v[72:73]
	v_cvt_pk_bf16_f32 v56, v56, v57
	v_cvt_pk_bf16_f32 v57, v58, v59
	v_pk_mul_f32 v[60:61], v[52:53], v[68:69] op_sel_hi:[1,0]
	v_pk_mul_f32 v[58:59], v[54:55], v[68:69] op_sel_hi:[1,0]
	v_exp_f32_e32 v60, v60
	v_exp_f32_e32 v61, v61
	v_exp_f32_e32 v58, v58
	v_exp_f32_e32 v59, v59
	v_fma_f32 v60, v60, v239, v239
	v_fma_f32 v61, v61, v239, v239
	v_rcp_f32_e32 v60, v60
	v_rcp_f32_e32 v61, v61
	v_fma_f32 v58, v58, v239, v239
	v_fma_f32 v59, v59, v239, v239
	v_rcp_f32_e32 v58, v58
	v_rcp_f32_e32 v59, v59
	s_nop 0
	v_pk_mul_f32 v[48:49], v[48:49], v[60:61]
	s_nop 0
	v_pk_mul_f32 v[50:51], v[50:51], v[58:59]
	v_cvt_pk_bf16_f32 v58, v48, v49
	v_mad_i64_i32 v[48:49], s[18:19], v67, s9, v[112:113]
	v_cvt_pk_bf16_f32 v59, v50, v51
	v_lshl_add_u64 v[48:49], v[48:49], 0, v[114:115]
	global_store_dwordx4 v[48:49], v[56:59], off
	v_fmamk_f32 v239, v236, 0x3a800000, v194
	s_nop 0
	v_rsq_f32_e32 v48, v239
	s_nop 0
	v_mov_b32_e32 v49, v48
	v_mul_f32_e32 v48, 0xbfb8aa3b, v49
	v_pk_mul_f32 v[54:55], v[44:45], v[48:49] op_sel_hi:[1,0]
	s_nop 0
	v_pk_mul_f32 v[52:53], v[46:47], v[48:49] op_sel_hi:[1,0]
	v_exp_f32_e32 v49, v54
	s_nop 0
	v_fma_f32 v49, v49, v239, v239
	v_rcp_f32_e32 v54, v49
	v_exp_f32_e32 v49, v55
	s_nop 0
	v_fma_f32 v49, v49, v239, v239
	v_rcp_f32_e32 v55, v49
	v_exp_f32_e32 v49, v52
	s_nop 0
	v_fma_f32 v49, v49, v239, v239
	v_rcp_f32_e32 v52, v49
	v_exp_f32_e32 v49, v53
	v_pk_mul_f32 v[40:41], v[40:41], v[54:55]
	v_fma_f32 v49, v49, v239, v239
	v_rcp_f32_e32 v53, v49
	v_cvt_pk_bf16_f32 v40, v40, v41
	s_nop 0
	v_pk_mul_f32 v[42:43], v[42:43], v[52:53]
	s_nop 0
	v_cvt_pk_bf16_f32 v41, v42, v43
	v_pk_mul_f32 v[44:45], v[36:37], v[48:49] op_sel_hi:[1,0]
	v_pk_mul_f32 v[42:43], v[38:39], v[48:49] op_sel_hi:[1,0]
	v_exp_f32_e32 v44, v44
	v_exp_f32_e32 v45, v45
	v_exp_f32_e32 v42, v42
	v_exp_f32_e32 v43, v43
	v_fma_f32 v44, v44, v239, v239
	v_fma_f32 v45, v45, v239, v239
	v_rcp_f32_e32 v44, v44
	v_rcp_f32_e32 v45, v45
	v_fma_f32 v42, v42, v239, v239
	v_fma_f32 v43, v43, v239, v239
	v_rcp_f32_e32 v42, v42
	v_rcp_f32_e32 v43, v43
	s_nop 0
	v_pk_mul_f32 v[32:33], v[32:33], v[44:45]
	s_nop 0
	v_pk_mul_f32 v[34:35], v[34:35], v[42:43]
	v_cvt_pk_bf16_f32 v42, v32, v33
	v_mad_i64_i32 v[32:33], s[18:19], v69, s9, v[112:113]
	v_cvt_pk_bf16_f32 v43, v34, v35
	v_lshl_add_u64 v[32:33], v[32:33], 0, v[114:115]
	global_store_dwordx4 v[32:33], v[40:43], off
	v_fmamk_f32 v239, v237, 0x3a800000, v194
	s_nop 0
	v_rsq_f32_e32 v32, v239
	s_nop 0
	v_mov_b32_e32 v33, v32
	v_mul_f32_e32 v32, 0xbfb8aa3b, v33
	v_pk_mul_f32 v[38:39], v[28:29], v[32:33] op_sel_hi:[1,0]
	s_nop 0
	v_pk_mul_f32 v[36:37], v[30:31], v[32:33] op_sel_hi:[1,0]
	v_exp_f32_e32 v33, v38
	s_nop 0
	v_fma_f32 v33, v33, v239, v239
	v_rcp_f32_e32 v38, v33
	v_exp_f32_e32 v33, v39
	s_nop 0
	v_fma_f32 v33, v33, v239, v239
	v_rcp_f32_e32 v39, v33
	v_exp_f32_e32 v33, v36
	s_nop 0
	v_fma_f32 v33, v33, v239, v239
	v_rcp_f32_e32 v36, v33
	v_exp_f32_e32 v33, v37
	v_pk_mul_f32 v[24:25], v[24:25], v[38:39]
	v_fma_f32 v33, v33, v239, v239
	v_rcp_f32_e32 v37, v33
	v_cvt_pk_bf16_f32 v24, v24, v25
	s_nop 0
	v_pk_mul_f32 v[26:27], v[26:27], v[36:37]
	s_nop 0
	v_cvt_pk_bf16_f32 v25, v26, v27
	v_pk_mul_f32 v[28:29], v[20:21], v[32:33] op_sel_hi:[1,0]
	v_pk_mul_f32 v[26:27], v[22:23], v[32:33] op_sel_hi:[1,0]
	v_exp_f32_e32 v28, v28
	v_exp_f32_e32 v29, v29
	v_exp_f32_e32 v26, v26
	v_exp_f32_e32 v27, v27
	v_fma_f32 v28, v28, v239, v239
	v_fma_f32 v29, v29, v239, v239
	v_rcp_f32_e32 v28, v28
	v_rcp_f32_e32 v29, v29
	v_fma_f32 v26, v26, v239, v239
	v_fma_f32 v27, v27, v239, v239
	v_rcp_f32_e32 v26, v26
	v_rcp_f32_e32 v27, v27
	s_nop 0
	v_pk_mul_f32 v[16:17], v[16:17], v[28:29]
	s_nop 0
	v_pk_mul_f32 v[18:19], v[18:19], v[26:27]
	v_cvt_pk_bf16_f32 v26, v16, v17
	v_mad_i64_i32 v[16:17], s[18:19], v66, s9, v[112:113]
	v_cvt_pk_bf16_f32 v27, v18, v19
	v_lshl_add_u64 v[16:17], v[16:17], 0, v[114:115]
	global_store_dwordx4 v[16:17], v[24:27], off
	v_fmamk_f32 v239, v238, 0x3a800000, v194
	s_nop 0
	v_rsq_f32_e32 v16, v239
	s_nop 0
	v_mov_b32_e32 v17, v16
	v_mul_f32_e32 v16, 0xbfb8aa3b, v17
	v_pk_mul_f32 v[22:23], v[12:13], v[16:17] op_sel_hi:[1,0]
	s_nop 0
	v_pk_mul_f32 v[20:21], v[14:15], v[16:17] op_sel_hi:[1,0]
	v_exp_f32_e32 v17, v22
	s_and_b64 vcc, exec, s[0:1]
	v_fma_f32 v17, v17, v239, v239
	v_rcp_f32_e32 v22, v17
	v_exp_f32_e32 v17, v23
	s_nop 0
	v_fma_f32 v17, v17, v239, v239
	v_rcp_f32_e32 v23, v17
	v_exp_f32_e32 v17, v20
	s_nop 0
	v_fma_f32 v17, v17, v239, v239
	v_rcp_f32_e32 v20, v17
	v_exp_f32_e32 v17, v21
	v_pk_mul_f32 v[8:9], v[8:9], v[22:23]
	v_fma_f32 v17, v17, v239, v239
	v_rcp_f32_e32 v21, v17
	v_cvt_pk_bf16_f32 v8, v8, v9
	s_nop 0
	v_pk_mul_f32 v[10:11], v[10:11], v[20:21]
	s_nop 0
	v_cvt_pk_bf16_f32 v9, v10, v11
	v_pk_mul_f32 v[12:13], v[4:5], v[16:17] op_sel_hi:[1,0]
	v_pk_mul_f32 v[10:11], v[6:7], v[16:17] op_sel_hi:[1,0]
	v_exp_f32_e32 v12, v12
	v_exp_f32_e32 v13, v13
	v_exp_f32_e32 v10, v10
	v_exp_f32_e32 v11, v11
	v_fma_f32 v12, v12, v239, v239
	v_fma_f32 v13, v13, v239, v239
	v_rcp_f32_e32 v12, v12
	v_rcp_f32_e32 v13, v13
	v_fma_f32 v10, v10, v239, v239
	v_fma_f32 v11, v11, v239, v239
	v_rcp_f32_e32 v10, v10
	v_rcp_f32_e32 v11, v11
	s_nop 0
	v_pk_mul_f32 v[0:1], v[0:1], v[12:13]
	s_nop 0
	v_pk_mul_f32 v[2:3], v[2:3], v[10:11]
	v_cvt_pk_bf16_f32 v10, v0, v1
	v_mad_i64_i32 v[0:1], s[18:19], v64, s9, v[112:113]
	v_cvt_pk_bf16_f32 v11, v2, v3
	v_lshl_add_u64 v[0:1], v[0:1], 0, v[114:115]
	s_mov_b64 s[18:19], s[14:15]
	global_store_dwordx4 v[0:1], v[8:11], off
	s_cbranch_vccz .LBB0_2801
	s_waitcnt vmcnt(0)
	s_cmpk_gt_u32 s25, 0xff
	s_cbranch_scc1 .LBB0_2808
	s_barrier
